# SSD phase: raised priority for waves 0-3 (state-update waves) instead of waves 4-7
# baseline (speedup 1.0000x reference)
; __device__ __forceinline__ void phase_ssd(const Params& P, int seg, unsigned char* smem) {
;     ...
;     if (__builtin_amdgcn_readfirstlane(tid) >= 256) __builtin_amdgcn_s_setprio(1);
; __device__ __forceinline__ void xcd_barrier(const XcdBarrier& b) {
;     ...
;     }
;     __syncthreads();
.LBB0_290:
	s_or_b64 exec, exec, s[0:1]
	s_mov_b64 s[0:1], s[80:81]
	v_mov_b32_e32 v5, v172
	s_waitcnt lgkmcnt(0)
	s_barrier
	s_nop 0
	v_readfirstlane_b32 s9, v5
	s_cmpk_lt_i32 s9, 0x100
	s_cbranch_scc0 .LBB0_292
	s_setprio 1
